# v59 + attention unit set-up: FoX F2 row and MoBA key means requested together with the unit's first K/V/Q loads (one memory round trip instead of 3-5 serialized ones)
# speedup vs baseline: 1.0107x; 1.0012x over previous
; #define LAS __attribute__((address_space(3)))
; template <bool MOBA>
; __device__ __forceinline__ void attn_unit(unsigned char* lds, LAS unsigned char* lds3, const Params& p, int b, int h, int qb) {
;     ...
;     const int skey = tid >> 3, sch = tid & 7;
;     const bf16_t* kp = Kg + (rowbase + skey) * DM + hcol + sch * 8; const bf16_t* vp = Vg + (rowbase + skey) * DM + hcol + sch * 8;
;     u32x4 kreg[2], vreg[2];
; #pragma unroll
;     for (int sb = 0; sb < 2; ++sb) { kreg[sb] = *(const u32x4*)(kp + (size_t)(NT - 1 - sb) * 64 * DM); vreg[sb] = *(const u32x4*)(vp + (size_t)(NT - 1 - sb) * 64 * DM); }
;     const size_t qrow0 = rowbase + qb * 256 + 32 * w;
;     bf16x8 qf[2][2];
; #pragma unroll
;     for (int jb = 0; jb < 2; ++jb)
; #pragma unroll
;         for (int ks = 0; ks < 2; ++ks) qf[jb][ks] = *(const bf16x8*)(Qg + (qrow0 + 16 * jb + fr) * DM + hcol + 32 * ks + 8 * fq);
;     __syncthreads();
;     float c31 = 0.f, bmax = -1.0e30f;
;     if (tid < 64) ((LAS float*)(lds3 + 73728 + 16384 + 2048))[64 + tid] = (tid < NT) ? ((const float*)(p.ws + WS_KNT))[((size_t)b * 16 + (MOBA ? 8 + h : h)) * 64 + tid] : 0.f;
;     LAS float* kpms = (LAS float*)(lds3 + 73728 + 16384 + 2048);
;     volatile LAS unsigned* dflag = (volatile LAS unsigned*)(lds3 + 73728 + 16384 + 2048 + 512);
;     if (!MOBA) {
;         const float* F2 = (const float*)(p.ws + WS_F2) + ((size_t)b * 8 + h) * SEQ;
;         for (int i = tid; i < 256 * (qb + 1); i += NTHREADS) Fs[i] = F2[i];
;         if (tid < 16) dflag[tid] = 0u;
;     } else {
;         const float* km = (const float*)(p.ws + WS_KMEAN) + (((size_t)b * 8 + h) * 16) * 64; const float* relb = p.in[I_RELB];
;         for (int i = tid; i < 16 * 64; i += NTHREADS) kms[i] = km[i];
.LBB0_367:
	s_lshr_b32 s6, s95, 10
	s_lshr_b32 s7, s95, 5
	s_lshl_b32 s5, s5, 1
	s_add_i32 s6, s6, s7
	s_add_i32 s6, s6, s5
	s_and_b32 s38, s2, 7
	s_and_b32 s90, s6, 7
	s_lshl_b32 s84, s38, 23
	s_and_b32 s39, s95, 7
	s_lshl_b32 s40, s90, 6
	s_cmp_gt_i32 s4, 3
	s_mov_b64 s[6:7], -1
	s_cbranch_scc0 .LBB0_503
	v_mov_b32_e32 v104, v174
	s_lshl_b32 s10, s39, 12
	v_ashrrev_i32_e32 v106, 3, v104
	s_mov_b32 s11, s75
	v_ashrrev_i32_e32 v107, 31, v106
	v_lshl_add_u64 v[2:3], s[10:11], 0, v[106:107]
	v_readlane_b32 s6, v255, 21
	v_lshlrev_b64 v[2:3], 11, v[2:3]
	v_readlane_b32 s7, v255, 22
	s_waitcnt vmcnt(0)
	v_lshlrev_b32_e32 v44, 3, v104
	v_readfirstlane_b32 s45, v104
	s_lshl_b32 s34, s86, 2
	v_lshl_add_u64 v[4:5], s[6:7], 0, v[2:3]
	s_lshl_b32 s6, s40, 1
	s_mov_b32 s7, s75
	v_and_b32_e32 v90, 56, v44
	v_lshl_add_u64 v[2:3], s[50:51], 0, v[2:3]
	v_lshl_add_u64 v[4:5], v[4:5], 0, s[6:7]
	v_lshlrev_b32_e32 v40, 1, v90
	v_mov_b32_e32 v41, v0
	v_lshl_add_u64 v[2:3], v[2:3], 0, s[6:7]
	s_or_b32 s44, s34, 3
	s_ashr_i32 s28, s45, 6
	v_lshl_add_u64 v[36:37], v[4:5], 0, v[40:41]
	v_lshl_add_u64 v[38:39], v[2:3], 0, v[40:41]
	s_lshl_b32 s74, s44, 17
	s_lshl_b32 s5, s86, 19
	s_lshl_b32 s42, s86, 8
	s_lshl_b32 s41, s28, 5
	s_or_b32 s4, s40, 0x200
	v_lshl_add_u64 v[2:3], v[36:37], 0, s[74:75]
	v_lshl_add_u64 v[4:5], v[38:39], 0, s[74:75]
	s_or_b32 s74, s5, 0x40000
	s_or_b32 s36, s10, s42
	s_ashr_i32 s5, s41, 31
	s_add_u32 s7, s36, s41
	v_and_b32_e32 v1, 15, v104
	s_addc_u32 s5, 0, s5
	global_load_dwordx4 v[32:35], v[2:3], off offset:1024
	global_load_dwordx4 v[20:23], v[4:5], off offset:1024
	v_lshl_add_u64 v[2:3], v[36:37], 0, s[74:75]
	v_or_b32_e32 v12, s7, v1
	v_mov_b32_e32 v13, s5
	v_lshl_add_u64 v[4:5], v[38:39], 0, s[74:75]
	global_load_dwordx4 v[28:31], v[2:3], off offset:1024
	global_load_dwordx4 v[24:27], v[4:5], off offset:1024
	v_and_b32_e32 v2, 48, v104
	v_mov_b32_e32 v3, v0
	v_lshlrev_b64 v[118:119], 11, v[12:13]
	v_or_b32_e32 v12, 16, v12
	v_lshl_add_u64 v[108:109], s[52:53], 0, v[2:3]
	v_lshlrev_b64 v[116:117], 11, v[12:13]
	v_lshl_add_u64 v[4:5], v[108:109], 0, v[118:119]
	s_lshl_b32 s74, s4, 1
	v_lshl_add_u64 v[12:13], v[108:109], 0, v[116:117]
	v_lshl_add_u64 v[4:5], v[4:5], 0, s[74:75]
	v_lshl_add_u64 v[12:13], v[12:13], 0, s[74:75]
	global_load_dwordx4 v[8:11], v[4:5], off
	s_nop 0
	global_load_dwordx4 v[4:7], v[4:5], off offset:64
	s_nop 0
	global_load_dwordx4 v[16:19], v[12:13], off
	s_nop 0
	global_load_dwordx4 v[12:15], v[12:13], off offset:64
	s_mov_b32 s37, s75
	s_add_i32 s43, s34, 4
	v_cmp_gt_i32_e64 s[8:9], 64, v104
	s_waitcnt lgkmcnt(0)
	s_barrier
	v_readlane_b32 s12, v255, 25
	s_lshl_b32 s16, s39, 15
	s_add_u32 s16, s12, s16
	v_readlane_b32 s12, v255, 26
	s_addc_u32 s17, s12, 0
	s_lshl_b32 s12, s90, 12
	s_add_u32 s16, s16, s12
	s_addc_u32 s17, s17, 0
	v_lshlrev_b32_e32 v48, 2, v104
	global_load_dword v46, v48, s[16:17]
	global_load_dword v47, v48, s[16:17] offset:2048
	s_and_saveexec_b64 s[12:13], s[8:9]
	s_cbranch_execz .LBB0_372
	v_cmp_gt_i32_e32 vcc, s43, v104
	v_mov_b32_e32 v3, 0
	s_and_saveexec_b64 s[14:15], vcc
	s_cbranch_execz .LBB0_371
	v_readlane_b32 s3, v255, 23
	s_add_u32 s4, s3, s10
	v_readlane_b32 s3, v255, 24
	s_addc_u32 s5, s3, 0
	s_lshl_b32 s7, s40, 2
	s_add_u32 s4, s4, s7
	s_addc_u32 s5, s5, 0
	v_ashrrev_i32_e32 v105, 31, v104
	v_lshl_add_u64 v[42:43], v[104:105], 2, s[4:5]
	global_load_dword v3, v[42:43], off offset:2048

; template <bool MOBA>
; __device__ __forceinline__ void attn_unit(unsigned char* lds, LAS unsigned char* lds3, const Params& p, int b, int h, int qb) {
;     ...
;         const float* km = (const float*)(p.ws + WS_KMEAN) + (((size_t)b * 8 + h) * 16) * 64; const float* relb = p.in[I_RELB];
;         for (int i = tid; i < 16 * 64; i += NTHREADS) kms[i] = km[i];
;         if (tid < 128) { int bk = tid; if (tid >= 16) { bk = 16 + (int)(logf((float)tid / 16.0f) / 2.0794415416798357f * 16.0f); bk = bk > 31 ? 31 : bk; } tbl[tid] = relb[bk * 8 + h] * LOG2E; }
.LBB0_372:
	s_or_b64 exec, exec, s[12:13]
	v_bfe_u32 v168, v104, 4, 2
	s_movk_i32 s4, 0x400
	v_and_b32_e32 v3, 63, v104
	v_lshlrev_b32_e32 v132, 3, v168
	v_cmp_gt_i32_e32 vcc, s4, v104
	s_and_saveexec_b64 s[10:11], vcc
	s_cbranch_execz .LBB0_380
	v_add_u32_e32 v48, 0x12000, v48
	s_waitcnt vmcnt(0)
	ds_write_b32 v48, v46
	ds_write_b32 v48, v47 offset:2048

; #define LAS __attribute__((address_space(3)))
; template <bool MOBA>
; __device__ __forceinline__ void attn_unit(unsigned char* lds, LAS unsigned char* lds3, const Params& p, int b, int h, int qb) {
;     ...
;     const int skey = tid >> 3, sch = tid & 7;
;     const bf16_t* kp = Kg + (rowbase + skey) * DM + hcol + sch * 8; const bf16_t* vp = Vg + (rowbase + skey) * DM + hcol + sch * 8;
;     u32x4 kreg[2], vreg[2];
; #pragma unroll
;     for (int sb = 0; sb < 2; ++sb) { kreg[sb] = *(const u32x4*)(kp + (size_t)(NT - 1 - sb) * 64 * DM); vreg[sb] = *(const u32x4*)(vp + (size_t)(NT - 1 - sb) * 64 * DM); }
;     const size_t qrow0 = rowbase + qb * 256 + 32 * w;
;     bf16x8 qf[2][2];
; #pragma unroll
;     for (int jb = 0; jb < 2; ++jb)
; #pragma unroll
;         for (int ks = 0; ks < 2; ++ks) qf[jb][ks] = *(const bf16x8*)(Qg + (qrow0 + 16 * jb + fr) * DM + hcol + 32 * ks + 8 * fq);
;     __syncthreads();
;     float c31 = 0.f, bmax = -1.0e30f;
;     if (tid < 64) ((LAS float*)(lds3 + 73728 + 16384 + 2048))[64 + tid] = (tid < NT) ? ((const float*)(p.ws + WS_KNT))[((size_t)b * 16 + (MOBA ? 8 + h : h)) * 64 + tid] : 0.f;
;     LAS float* kpms = (LAS float*)(lds3 + 73728 + 16384 + 2048);
;     volatile LAS unsigned* dflag = (volatile LAS unsigned*)(lds3 + 73728 + 16384 + 2048 + 512);
;     if (!MOBA) {
;         const float* F2 = (const float*)(p.ws + WS_F2) + ((size_t)b * 8 + h) * SEQ;
;         for (int i = tid; i < 256 * (qb + 1); i += NTHREADS) Fs[i] = F2[i];
.LBB0_503:
	s_and_b64 vcc, exec, s[6:7]
	s_cbranch_vccz .LBB0_360
	v_mov_b32_e32 v42, v174
	s_lshl_b32 s74, s39, 12
	s_waitcnt vmcnt(0)
	v_ashrrev_i32_e32 v44, 3, v42
	v_ashrrev_i32_e32 v45, 31, v44
	v_lshl_add_u64 v[2:3], s[74:75], 0, v[44:45]
	v_readlane_b32 s6, v255, 21
	s_add_i32 s5, s86, 1
	v_lshlrev_b64 v[2:3], 11, v[2:3]
	v_readlane_b32 s7, v255, 22
	v_lshlrev_b32_e32 v6, 3, v42
	s_lshl_b32 s8, s5, 2
	v_lshl_add_u64 v[4:5], s[6:7], 0, v[2:3]
	s_lshl_b32 s82, s40, 1
	s_mov_b32 s83, s75
	v_and_b32_e32 v46, 56, v6
	v_lshl_add_u64 v[2:3], s[50:51], 0, v[2:3]
	v_lshl_add_u64 v[4:5], v[4:5], 0, s[82:83]
	v_lshlrev_b32_e32 v36, 1, v46
	v_mov_b32_e32 v37, v0
	v_lshl_add_u64 v[2:3], v[2:3], 0, s[82:83]
	s_add_i32 s6, s8, -1
	s_mov_b32 s7, s75
	v_readfirstlane_b32 s4, v42
	v_lshl_add_u64 v[6:7], v[4:5], 0, v[36:37]
	v_lshl_add_u64 v[8:9], v[2:3], 0, v[36:37]
	s_lshl_b64 s[10:11], s[6:7], 17
	v_lshl_add_u64 v[2:3], v[6:7], 0, s[10:11]
	v_lshl_add_u64 v[10:11], v[8:9], 0, s[10:11]
	s_add_i32 s10, s8, -2
	s_mov_b32 s11, s75
	s_ashr_i32 s20, s4, 6
	s_lshl_b64 s[10:11], s[10:11], 17
	s_lshl_b32 s21, s86, 8
	s_lshl_b32 s7, s20, 5
	v_lshl_add_u64 v[6:7], v[6:7], 0, s[10:11]
	v_lshl_add_u64 v[8:9], v[8:9], 0, s[10:11]
	s_or_b32 s9, s74, s21
	s_ashr_i32 s10, s7, 31
	s_add_u32 s9, s9, s7
	v_and_b32_e32 v1, 15, v42
	s_addc_u32 s12, 0, s10
	s_add_u32 s10, s52, s82
	v_or_b32_e32 v20, s9, v1
	v_mov_b32_e32 v21, s12
	s_addc_u32 s11, s53, 0
	v_and_b32_e32 v34, 48, v42
	v_mov_b32_e32 v35, v0
	v_lshlrev_b64 v[108:109], 11, v[20:21]
	v_or_b32_e32 v20, 16, v20
	v_lshl_add_u64 v[18:19], s[10:11], 0, v[34:35]
	v_lshlrev_b64 v[106:107], 11, v[20:21]
	global_load_dwordx4 v[2:5], v[2:3], off
	s_nop 0
	global_load_dwordx4 v[30:33], v[10:11], off
	v_lshl_add_u64 v[10:11], v[18:19], 0, v[108:109]
	v_lshl_add_u64 v[22:23], v[18:19], 0, v[106:107]
	global_load_dwordx4 v[14:17], v[6:7], off
	global_load_dwordx4 v[26:29], v[8:9], off
	s_nop 0
	global_load_dwordx4 v[6:9], v[10:11], off
	s_nop 0
	global_load_dwordx4 v[10:13], v[10:11], off offset:64
	s_nop 0
	global_load_dwordx4 v[18:21], v[22:23], off
	s_nop 0
	global_load_dwordx4 v[22:25], v[22:23], off offset:64
	v_cmp_gt_i32_e32 vcc, 64, v42
	s_waitcnt lgkmcnt(0)
	s_barrier
	v_readlane_b32 s12, v255, 27
	s_lshl_b32 s16, s39, 17
	s_add_u32 s16, s12, s16
	v_readlane_b32 s12, v255, 28
	s_addc_u32 s17, s12, 0
	s_lshl_b32 s12, s90, 14
	s_add_u32 s16, s16, s12
	s_addc_u32 s17, s17, 0
	v_lshlrev_b32_e32 v53, 2, v42
	global_load_dword v40, v53, s[16:17]
	global_load_dword v41, v53, s[16:17] offset:2048
	s_add_u32 s16, s16, 0x1000
	s_addc_u32 s17, s17, 0
	global_load_dword v47, v53, s[16:17]
	global_load_dword v48, v53, s[16:17] offset:2048
	s_add_u32 s16, s16, 0x1000
	s_addc_u32 s17, s17, 0
	global_load_dword v49, v53, s[16:17]
	global_load_dword v50, v53, s[16:17] offset:2048
	s_add_u32 s16, s16, 0x1000
	s_addc_u32 s17, s17, 0
	global_load_dword v51, v53, s[16:17]
	global_load_dword v52, v53, s[16:17] offset:2048
	s_and_saveexec_b64 s[10:11], vcc
	s_cbranch_execz .LBB0_508
	v_cmp_gt_i32_e64 s[8:9], s8, v42
	v_mov_b32_e32 v35, 0
	s_and_saveexec_b64 s[12:13], s[8:9]
	s_cbranch_execz .LBB0_507
	v_readlane_b32 s3, v255, 23
	s_add_u32 s8, s3, s74
	v_readlane_b32 s3, v255, 24
	s_addc_u32 s9, s3, 0
	s_lshl_b32 s14, s40, 2
	s_add_u32 s8, s8, s14
	s_addc_u32 s9, s9, 0
	v_ashrrev_i32_e32 v43, 31, v42
	v_lshl_add_u64 v[38:39], v[42:43], 2, s[8:9]
	global_load_dword v35, v[38:39], off

; #define LAS __attribute__((address_space(3)))
; template <bool MOBA>
; __device__ __forceinline__ void attn_unit(unsigned char* lds, LAS unsigned char* lds3, const Params& p, int b, int h, int qb) {
;     ...
;     if (!MOBA) {
;         const float* F2 = (const float*)(p.ws + WS_F2) + ((size_t)b * 8 + h) * SEQ;
;         for (int i = tid; i < 256 * (qb + 1); i += NTHREADS) Fs[i] = F2[i];
;         if (tid < 16) dflag[tid] = 0u;
;     } else {
;         const float* km = (const float*)(p.ws + WS_KMEAN) + (((size_t)b * 8 + h) * 16) * 64; const float* relb = p.in[I_RELB];
;         for (int i = tid; i < 16 * 64; i += NTHREADS) kms[i] = km[i];
;         if (tid < 128) { int bk = tid; if (tid >= 16) { bk = 16 + (int)(logf((float)tid / 16.0f) / 2.0794415416798357f * 16.0f); bk = bk > 31 ? 31 : bk; } tbl[tid] = relb[bk * 8 + h] * LOG2E; }
;         c31 = relb[31 * 8 + h] * LOG2E;
;         for (int bk = 0; bk < 32; ++bk) bmax = fmaxf(bmax, relb[bk * 8 + h] * LOG2E);
;         __syncthreads();
;         if (tid < 256) {
;             const bf16_t* qp = Qg + (rowbase + qb * 256 + tid) * DM + hcol; float qv[64];
; #pragma unroll
;             for (int c = 0; c < 8; ++c) { const u32x4 v = *(const u32x4*)(qp + c * 8);
; #pragma unroll
;                 for (int j = 0; j < 4; ++j) { qv[c * 8 + 2 * j] = bf_lo(v[j]); qv[c * 8 + 2 * j + 1] = bf_hi(v[j]); } }
;             float v1 = -INFINITY, v2 = -INFINITY, v3 = -INFINITY; int i1 = -1, i2 = -1, i3 = -1;
;             for (int j = 0; j < qb; ++j) { float d = 0.f;
; #pragma unroll
;                 for (int c = 0; c < 16; ++c) { const f32x4 kv = *(const LAS f32x4*)(kms + j * 64 + c * 4); d += qv[4 * c] * kv[0] + qv[4 * c + 1] * kv[1] + qv[4 * c + 2] * kv[2] + qv[4 * c + 3] * kv[3]; }
;                 if (d > v1) { v3 = v2; i3 = i2; v2 = v1; i2 = i1; v1 = d; i1 = j; } else if (d > v2) { v3 = v2; i3 = i2; v2 = d; i2 = j; } else if (d > v3) { v3 = d; i3 = j; } }
;             unsigned mask = 0u; if (i1 >= 0) mask |= 1u << i1; if (i2 >= 0) mask |= 1u << i2; if (i3 >= 0) mask |= 1u << i3;
;             sel[tid] = mask | (1u << qb);
;         }
;     }
;     const int vswz = (skey ^ (sch << 3));
;     ...
;     ATT_STORE(0);
;     __syncthreads();
;     if (tid < 64) { float pm = 0.f; for (int t = 0; t <= tid; ++t) pm = fmaxf(pm, kpms[64 + t]); kpms[tid] = sqrtf(pm) * 1.002f; }
.LBB0_508:
	s_or_b64 exec, exec, s[10:11]
	v_bfe_u32 v37, v42, 4, 2
	s_lshl_b32 s18, s5, 8
	v_and_b32_e32 v35, 63, v42
	v_lshlrev_b32_e32 v114, 3, v37
	v_cmp_gt_i32_e64 s[8:9], s18, v42
	s_and_saveexec_b64 s[10:11], s[8:9]
	s_cbranch_execz .LBB0_516
	v_add_u32_e32 v53, 0x12000, v53
	s_waitcnt vmcnt(0)
	ds_write_b32 v53, v40
	v_mov_b32_e32 v38, v42
	v_add_u32_e32 v38, 0x200, v38
	v_cmp_gt_i32_e64 s[8:9], s18, v38
	s_and_b64 exec, exec, s[8:9]
	ds_write_b32 v53, v41 offset:2048
	v_add_u32_e32 v38, 0x200, v38
	v_cmp_gt_i32_e64 s[8:9], s18, v38
	s_and_b64 exec, exec, s[8:9]
	ds_write_b32 v53, v47 offset:4096
	v_add_u32_e32 v38, 0x200, v38
	v_cmp_gt_i32_e64 s[8:9], s18, v38
	s_and_b64 exec, exec, s[8:9]
	ds_write_b32 v53, v48 offset:6144
	v_add_u32_e32 v38, 0x200, v38
	v_cmp_gt_i32_e64 s[8:9], s18, v38
	s_and_b64 exec, exec, s[8:9]
	ds_write_b32 v53, v49 offset:8192
	v_add_u32_e32 v38, 0x200, v38
	v_cmp_gt_i32_e64 s[8:9], s18, v38
	s_and_b64 exec, exec, s[8:9]
	ds_write_b32 v53, v50 offset:10240
	v_add_u32_e32 v38, 0x200, v38
	v_cmp_gt_i32_e64 s[8:9], s18, v38
	s_and_b64 exec, exec, s[8:9]
	ds_write_b32 v53, v51 offset:12288
	v_add_u32_e32 v38, 0x200, v38
	v_cmp_gt_i32_e64 s[8:9], s18, v38
	s_and_b64 exec, exec, s[8:9]
	ds_write_b32 v53, v52 offset:14336
.LBB0_516:
	s_waitcnt vmcnt(0)
	s_or_b64 exec, exec, s[10:11]
	v_cmp_gt_i32_e64 s[8:9], 16, v42
	v_lshl_add_u32 v38, v42, 2, 0
	s_and_saveexec_b64 s[10:11], s[8:9]
	v_add_u32_e32 v39, 0x16a00, v38
	ds_write_b32 v39, v0
	s_or_b64 exec, exec, s[10:11]
	s_movk_i32 s3, 0x90
	v_xor_b32_e32 v39, v46, v44
	v_mul_lo_u32 v40, v44, s3
	v_add3_u32 v115, 0, v40, v36
	v_mul_u32_u24_e32 v36, 0x90, v46
	v_lshlrev_b32_e32 v39, 1, v39
	v_add3_u32 v116, 0, v36, v39
	s_waitcnt vmcnt(7)
	ds_write_b128 v115, v[2:5]
	s_waitcnt vmcnt(6)
	ds_write_b16 v116, v30 offset:36864
	ds_write_b16_d16_hi v116, v30 offset:37008
	ds_write_b16 v116, v31 offset:37152
	ds_write_b16_d16_hi v116, v31 offset:37296
	ds_write_b16 v116, v32 offset:37440
	ds_write_b16_d16_hi v116, v32 offset:37584
	ds_write_b16 v116, v33 offset:37728
	ds_write_b16_d16_hi v116, v33 offset:37872
	s_waitcnt vmcnt(5)
	ds_write_b128 v115, v[14:17] offset:9216
	s_waitcnt vmcnt(4)
	ds_write_b16 v116, v26 offset:46080
	ds_write_b16_d16_hi v116, v26 offset:46224
	ds_write_b16 v116, v27 offset:46368
	ds_write_b16_d16_hi v116, v27 offset:46512
	ds_write_b16 v116, v28 offset:46656
	ds_write_b16_d16_hi v116, v28 offset:46800
	ds_write_b16 v116, v29 offset:46944
	ds_write_b16_d16_hi v116, v29 offset:47088
	s_waitcnt lgkmcnt(0)
	s_barrier
	s_and_saveexec_b64 s[10:11], vcc
	s_cbranch_execz .LBB0_530
	v_cmp_lt_i32_e32 vcc, -1, v42
	v_mov_b32_e32 v36, 0
	s_and_saveexec_b64 s[12:13], vcc
	s_cbranch_execz .LBB0_529
	v_add_u32_e32 v39, 0x16900, v38
	ds_read_b32 v40, v39
	s_mov_b64 s[8:9], exec
	s_waitcnt lgkmcnt(0)
	v_max_f32_e32 v40, v40, v40
	s_nop 1
	v_max_f32_dpp v40, v40, v40 row_shr:1 row_mask:0xf bank_mask:0xf bound_ctrl:1
	s_nop 1
	v_max_f32_dpp v40, v40, v40 row_shr:2 row_mask:0xf bank_mask:0xf bound_ctrl:1
	s_nop 1
	v_max_f32_dpp v40, v40, v40 row_shr:4 row_mask:0xf bank_mask:0xf bound_ctrl:1
	s_nop 1
	v_max_f32_dpp v40, v40, v40 row_shr:8 row_mask:0xf bank_mask:0xf bound_ctrl:1
	s_nop 1
	v_max_f32_dpp v40, v40, v40 row_bcast:15 row_mask:0xa bank_mask:0xf
	s_nop 1
	v_max_f32_dpp v40, v40, v40 row_bcast:31 row_mask:0xc bank_mask:0xf
	s_nop 1
